# P4 y_ret tiles: first epilogue batch (4 o_ret pieces + 2 SS vectors) prefetched in the last K-trip, on top of the P5/P6 prefetch
# baseline (speedup 1.0000x reference)
.LBB0_689:
	ds_read_b128 v[146:149], v160
	ds_read_b128 v[150:153], v160 offset:1024
	ds_read_b128 v[154:157], v160 offset:2048
	ds_read_b128 v[164:167], v160 offset:3072
	ds_read_b128 v[168:171], v161
	ds_read_b128 v[172:175], v161 offset:1024
	ds_read_b128 v[176:179], v161 offset:2048
	ds_read_b128 v[180:183], v161 offset:3072
	s_add_u32 s48, s81, s10
	s_addc_u32 s49, s82, 0
	s_add_u32 s85, s83, s10
	s_addc_u32 s86, s84, 0
	s_cmp_eq_u32 s10, s0
	s_cselect_b32 s51, s5, s49
	s_cselect_b32 s50, s43, s48
	s_cselect_b32 s49, s41, s86
	s_cselect_b32 s48, s79, s85
	s_add_i32 s86, s56, 0xc000
	v_lshl_add_u64 v[216:217], v[130:131], 0, s[10:11]
	s_mov_b32 m0, s86
	s_add_i32 s85, s56, 0xe000
	ds_read_b128 v[184:187], v162
	ds_read_b128 v[188:191], v162 offset:1024
	ds_read_b128 v[192:195], v162 offset:2048
	ds_read_b128 v[196:199], v162 offset:3072
	ds_read_b128 v[200:203], v162 offset:4096
	ds_read_b128 v[204:207], v162 offset:5120
	ds_read_b128 v[208:211], v162 offset:6144
	ds_read_b128 v[212:215], v162 offset:7168
	global_load_lds_dwordx4 v[216:217], off
	v_lshl_add_u64 v[216:217], v[132:133], 0, s[10:11]
	s_mov_b32 m0, s85
	s_nop 0
	global_load_lds_dwordx4 v[216:217], off
	s_waitcnt vmcnt(8)
	s_waitcnt lgkmcnt(0)
	s_barrier
	s_setprio 1
	s_waitcnt lgkmcnt(0)
	v_mfma_f32_16x16x32_bf16 v[126:129], v[146:149], v[184:187], v[126:129]
	v_mfma_f32_16x16x32_bf16 v[122:125], v[154:157], v[184:187], v[122:125]
	v_mfma_f32_16x16x32_bf16 v[110:113], v[146:149], v[192:195], v[110:113]
	v_mfma_f32_16x16x32_bf16 v[106:109], v[154:157], v[192:195], v[106:109]
	v_mfma_f32_16x16x32_bf16 v[94:97], v[146:149], v[200:203], v[94:97]
	v_mfma_f32_16x16x32_bf16 v[90:93], v[154:157], v[200:203], v[90:93]
	v_mfma_f32_16x16x32_bf16 v[78:81], v[146:149], v[208:211], v[78:81]
	v_mfma_f32_16x16x32_bf16 v[74:77], v[154:157], v[208:211], v[74:77]
	v_mfma_f32_16x16x32_bf16 v[126:129], v[150:153], v[188:191], v[126:129]
	v_mfma_f32_16x16x32_bf16 v[122:125], v[164:167], v[188:191], v[122:125]
	v_mfma_f32_16x16x32_bf16 v[110:113], v[150:153], v[196:199], v[110:113]
	v_mfma_f32_16x16x32_bf16 v[106:109], v[164:167], v[196:199], v[106:109]
	v_mfma_f32_16x16x32_bf16 v[94:97], v[150:153], v[204:207], v[94:97]
	v_mfma_f32_16x16x32_bf16 v[90:93], v[164:167], v[204:207], v[90:93]
	v_mfma_f32_16x16x32_bf16 v[78:81], v[150:153], v[212:215], v[78:81]
	v_mfma_f32_16x16x32_bf16 v[74:77], v[164:167], v[212:215], v[74:77]
	s_setprio 0
	s_setprio 1
	v_mfma_f32_16x16x32_bf16 v[118:121], v[168:171], v[184:187], v[118:121]
	v_mfma_f32_16x16x32_bf16 v[114:117], v[176:179], v[184:187], v[114:117]
	v_mfma_f32_16x16x32_bf16 v[102:105], v[168:171], v[192:195], v[102:105]
	v_mfma_f32_16x16x32_bf16 v[98:101], v[176:179], v[192:195], v[98:101]
	v_mfma_f32_16x16x32_bf16 v[86:89], v[168:171], v[200:203], v[86:89]
	v_mfma_f32_16x16x32_bf16 v[82:85], v[176:179], v[200:203], v[82:85]
	v_mfma_f32_16x16x32_bf16 v[70:73], v[168:171], v[208:211], v[70:73]
	v_mfma_f32_16x16x32_bf16 v[66:69], v[176:179], v[208:211], v[66:69]
	v_mfma_f32_16x16x32_bf16 v[118:121], v[172:175], v[188:191], v[118:121]
	v_mfma_f32_16x16x32_bf16 v[114:117], v[180:183], v[188:191], v[114:117]
	v_mfma_f32_16x16x32_bf16 v[102:105], v[172:175], v[196:199], v[102:105]
	v_mfma_f32_16x16x32_bf16 v[98:101], v[180:183], v[196:199], v[98:101]
	v_mfma_f32_16x16x32_bf16 v[86:89], v[172:175], v[204:207], v[86:89]
	v_mfma_f32_16x16x32_bf16 v[82:85], v[180:183], v[204:207], v[82:85]
	v_mfma_f32_16x16x32_bf16 v[70:73], v[172:175], v[212:215], v[70:73]
	v_mfma_f32_16x16x32_bf16 v[66:69], v[180:183], v[212:215], v[66:69]
	s_setprio 0
	s_barrier
	s_add_i32 s87, s69, s55
	v_lshl_add_u64 v[216:217], s[48:49], 0, v[136:137]
	s_mov_b32 m0, s87
	ds_read_b128 v[184:187], v162 offset:16384
	ds_read_b128 v[188:191], v162 offset:17408
	ds_read_b128 v[192:195], v162 offset:18432
	ds_read_b128 v[196:199], v162 offset:19456
	ds_read_b128 v[200:203], v162 offset:20480
	ds_read_b128 v[204:207], v162 offset:21504
	ds_read_b128 v[208:211], v162 offset:22528
	ds_read_b128 v[212:215], v162 offset:23552
	global_load_lds_dwordx4 v[216:217], off
	s_add_i32 m0, s87, 0x2000
	s_add_u32 s88, s48, 0x40000
	v_lshl_add_u64 v[218:219], s[48:49], 0, v[140:141]
	s_addc_u32 s89, s49, 0
	s_add_i32 s87, s70, s55
	global_load_lds_dwordx4 v[218:219], off
	v_lshl_add_u64 v[220:221], s[88:89], 0, v[136:137]
	s_mov_b32 m0, s87
	v_lshl_add_u64 v[222:223], s[50:51], 0, v[138:139]
	global_load_lds_dwordx4 v[220:221], off
	v_lshl_add_u64 v[220:221], s[88:89], 0, v[140:141]
	s_add_i32 m0, s87, 0x2000
	s_nop 0
	global_load_lds_dwordx4 v[220:221], off
	v_lshl_add_u64 v[220:221], s[50:51], 0, v[134:135]
	s_mov_b32 m0, s56
	s_nop 0
	global_load_lds_dwordx4 v[220:221], off
	s_mov_b32 m0, s57
	s_nop 0
	global_load_lds_dwordx4 v[222:223], off
	s_waitcnt vmcnt(8)
	s_waitcnt lgkmcnt(0)
	s_barrier
	s_setprio 1
	s_waitcnt lgkmcnt(0)
	v_mfma_f32_16x16x32_bf16 v[62:65], v[146:149], v[184:187], v[62:65]
	v_mfma_f32_16x16x32_bf16 v[58:61], v[154:157], v[184:187], v[58:61]
	v_mfma_f32_16x16x32_bf16 v[46:49], v[146:149], v[192:195], v[46:49]
	v_mfma_f32_16x16x32_bf16 v[42:45], v[154:157], v[192:195], v[42:45]
	v_mfma_f32_16x16x32_bf16 v[6:9], v[146:149], v[200:203], v[6:9]
	v_mfma_f32_16x16x32_bf16 v[2:5], v[154:157], v[200:203], v[2:5]
	v_mfma_f32_16x16x32_bf16 v[22:25], v[146:149], v[208:211], v[22:25]
	v_mfma_f32_16x16x32_bf16 v[18:21], v[154:157], v[208:211], v[18:21]
	v_mfma_f32_16x16x32_bf16 v[62:65], v[150:153], v[188:191], v[62:65]
	v_mfma_f32_16x16x32_bf16 v[58:61], v[164:167], v[188:191], v[58:61]
	v_mfma_f32_16x16x32_bf16 v[46:49], v[150:153], v[196:199], v[46:49]
	v_mfma_f32_16x16x32_bf16 v[42:45], v[164:167], v[196:199], v[42:45]
	v_mfma_f32_16x16x32_bf16 v[6:9], v[150:153], v[204:207], v[6:9]
	v_mfma_f32_16x16x32_bf16 v[2:5], v[164:167], v[204:207], v[2:5]
	v_mfma_f32_16x16x32_bf16 v[22:25], v[150:153], v[212:215], v[22:25]
	v_mfma_f32_16x16x32_bf16 v[18:21], v[164:167], v[212:215], v[18:21]
	s_setprio 0
	s_setprio 1
	v_mfma_f32_16x16x32_bf16 v[54:57], v[168:171], v[184:187], v[54:57]
	v_mfma_f32_16x16x32_bf16 v[50:53], v[176:179], v[184:187], v[50:53]
	v_mfma_f32_16x16x32_bf16 v[38:41], v[168:171], v[192:195], v[38:41]
	v_mfma_f32_16x16x32_bf16 v[34:37], v[176:179], v[192:195], v[34:37]
	v_mfma_f32_16x16x32_bf16 v[14:17], v[168:171], v[200:203], v[14:17]
	v_mfma_f32_16x16x32_bf16 v[10:13], v[176:179], v[200:203], v[10:13]
	v_mfma_f32_16x16x32_bf16 v[30:33], v[168:171], v[208:211], v[30:33]
	v_mfma_f32_16x16x32_bf16 v[26:29], v[176:179], v[208:211], v[26:29]
	v_mfma_f32_16x16x32_bf16 v[54:57], v[172:175], v[188:191], v[54:57]
	v_mfma_f32_16x16x32_bf16 v[50:53], v[180:183], v[188:191], v[50:53]
	v_mfma_f32_16x16x32_bf16 v[38:41], v[172:175], v[196:199], v[38:41]
	v_mfma_f32_16x16x32_bf16 v[34:37], v[180:183], v[196:199], v[34:37]
	v_mfma_f32_16x16x32_bf16 v[14:17], v[172:175], v[204:207], v[14:17]
	v_mfma_f32_16x16x32_bf16 v[10:13], v[180:183], v[204:207], v[10:13]
	v_mfma_f32_16x16x32_bf16 v[30:33], v[172:175], v[212:215], v[30:33]
	v_mfma_f32_16x16x32_bf16 v[26:29], v[180:183], v[212:215], v[26:29]
	s_setprio 0
	s_barrier
	s_cmp_lg_u32 s10, s0
	s_cbranch_scc1 .Lmy_p4_nox
	s_cmp_gt_u32 s78, 7
	s_cbranch_scc1 .Lmy_p4_nox
	s_lshl_b32 s98, s4, 8
	s_add_i32 s98, s98, s62
	v_add_u32_e32 v252, s98, v1
	s_lshl_b32 s98, s78, 8
	s_or_b32 s98, s98, s63
	v_lshl_add_u32 v250, v158, 3, s98
	v_lshlrev_b32_e32 v250, 1, v250
	v_lshl_add_u32 v250, v252, 12, v250
	v_add_u32_e32 v250, 0xfa00000, v250
	s_lshl_b32 s98, s78, 3
	s_and_b32 s98, s98, -16
	s_lshl_b32 s98, s98, 2
	v_lshl_add_u32 v251, v158, 4, s98
	v_lshl_add_u32 v251, v252, 8, v251
	global_load_dwordx4 v[226:229], v250, s[8:9]
	global_load_dwordx4 v[230:233], v251, s[60:61]
	v_add_u32_e32 v253, 0x1000, v251
	global_load_dwordx4 v[234:237], v253, s[60:61]
	global_load_dwordx4 v[238:241], v250, s[8:9] offset:256
	v_add_u32_e32 v250, 0x10000, v250
	global_load_dwordx4 v[242:245], v250, s[8:9]
	global_load_dwordx4 v[246:249], v250, s[8:9] offset:256
.Lmy_p4_nox:
	s_add_i32 s87, 0, 0x18000
	v_add_u32_e32 v163, s87, v159
	s_add_i32 s88, 0, 0x1c000
	ds_read_b128 v[146:149], v163
	ds_read_b128 v[150:153], v163 offset:1024
	ds_read_b128 v[154:157], v163 offset:2048
	ds_read_b128 v[164:167], v163 offset:3072
	v_add_u32_e32 v163, s88, v159
	ds_read_b128 v[168:171], v163
	ds_read_b128 v[172:175], v163 offset:1024
	ds_read_b128 v[176:179], v163 offset:2048
	ds_read_b128 v[180:183], v163 offset:3072
	s_add_u32 s50, s50, 0x40000
	s_addc_u32 s51, s51, 0
	s_mov_b32 m0, s58
	v_lshl_add_u64 v[224:225], s[50:51], 0, v[134:135]
	ds_read_b128 v[184:187], v162 offset:32768
	ds_read_b128 v[188:191], v162 offset:33792
	ds_read_b128 v[192:195], v162 offset:34816
	ds_read_b128 v[196:199], v162 offset:35840
	ds_read_b128 v[200:203], v162 offset:36864
	ds_read_b128 v[204:207], v162 offset:37888
	ds_read_b128 v[208:211], v162 offset:38912
	ds_read_b128 v[212:215], v162 offset:39936
	global_load_lds_dwordx4 v[224:225], off
	v_lshl_add_u64 v[224:225], s[50:51], 0, v[138:139]
	s_mov_b32 m0, s59
	s_nop 0
	global_load_lds_dwordx4 v[224:225], off
	s_cmp_lg_u32 s10, s0
	s_cbranch_scc1 .Lmy_p4_wc_n
	s_cmp_gt_u32 s78, 7
	s_cbranch_scc1 .Lmy_p4_wc_n
	s_waitcnt vmcnt(14)
	s_branch .Lmy_p4_wc_done

.Lmy_p4_wc_done:
	s_waitcnt lgkmcnt(0)
	s_barrier
	s_setprio 1
	s_waitcnt lgkmcnt(0)
	v_mfma_f32_16x16x32_bf16 v[126:129], v[146:149], v[184:187], v[126:129]
	v_mfma_f32_16x16x32_bf16 v[122:125], v[154:157], v[184:187], v[122:125]
	v_mfma_f32_16x16x32_bf16 v[110:113], v[146:149], v[192:195], v[110:113]
	v_mfma_f32_16x16x32_bf16 v[106:109], v[154:157], v[192:195], v[106:109]
	v_mfma_f32_16x16x32_bf16 v[94:97], v[146:149], v[200:203], v[94:97]
	v_mfma_f32_16x16x32_bf16 v[90:93], v[154:157], v[200:203], v[90:93]
	v_mfma_f32_16x16x32_bf16 v[78:81], v[146:149], v[208:211], v[78:81]
	v_mfma_f32_16x16x32_bf16 v[74:77], v[154:157], v[208:211], v[74:77]
	v_mfma_f32_16x16x32_bf16 v[126:129], v[150:153], v[188:191], v[126:129]
	v_mfma_f32_16x16x32_bf16 v[122:125], v[164:167], v[188:191], v[122:125]
	v_mfma_f32_16x16x32_bf16 v[110:113], v[150:153], v[196:199], v[110:113]
	v_mfma_f32_16x16x32_bf16 v[106:109], v[164:167], v[196:199], v[106:109]
	v_mfma_f32_16x16x32_bf16 v[94:97], v[150:153], v[204:207], v[94:97]
	v_mfma_f32_16x16x32_bf16 v[90:93], v[164:167], v[204:207], v[90:93]
	v_mfma_f32_16x16x32_bf16 v[78:81], v[150:153], v[212:215], v[78:81]
	v_mfma_f32_16x16x32_bf16 v[74:77], v[164:167], v[212:215], v[74:77]
	s_setprio 0
	s_setprio 1
	v_mfma_f32_16x16x32_bf16 v[118:121], v[168:171], v[184:187], v[118:121]
	v_mfma_f32_16x16x32_bf16 v[114:117], v[176:179], v[184:187], v[114:117]
	v_mfma_f32_16x16x32_bf16 v[102:105], v[168:171], v[192:195], v[102:105]
	v_mfma_f32_16x16x32_bf16 v[98:101], v[176:179], v[192:195], v[98:101]
	v_mfma_f32_16x16x32_bf16 v[86:89], v[168:171], v[200:203], v[86:89]
	v_mfma_f32_16x16x32_bf16 v[82:85], v[176:179], v[200:203], v[82:85]
	v_mfma_f32_16x16x32_bf16 v[70:73], v[168:171], v[208:211], v[70:73]
	v_mfma_f32_16x16x32_bf16 v[66:69], v[176:179], v[208:211], v[66:69]
	v_mfma_f32_16x16x32_bf16 v[118:121], v[172:175], v[188:191], v[118:121]
	v_mfma_f32_16x16x32_bf16 v[114:117], v[180:183], v[188:191], v[114:117]
	v_mfma_f32_16x16x32_bf16 v[102:105], v[172:175], v[196:199], v[102:105]
	v_mfma_f32_16x16x32_bf16 v[98:101], v[180:183], v[196:199], v[98:101]
	v_mfma_f32_16x16x32_bf16 v[86:89], v[172:175], v[204:207], v[86:89]
	v_mfma_f32_16x16x32_bf16 v[82:85], v[180:183], v[204:207], v[82:85]
	v_mfma_f32_16x16x32_bf16 v[70:73], v[172:175], v[212:215], v[70:73]
	v_mfma_f32_16x16x32_bf16 v[66:69], v[180:183], v[212:215], v[66:69]
	s_setprio 0
	s_barrier
	s_add_i32 s50, s87, s55
	v_lshl_add_u64 v[216:217], v[216:217], 0, s[14:15]
	s_mov_b32 m0, s50
	ds_read_b128 v[184:187], v162 offset:49152
	ds_read_b128 v[188:191], v162 offset:50176
	ds_read_b128 v[192:195], v162 offset:51200
	ds_read_b128 v[196:199], v162 offset:52224
	ds_read_b128 v[200:203], v162 offset:53248
	ds_read_b128 v[204:207], v162 offset:54272
	ds_read_b128 v[208:211], v162 offset:55296
	ds_read_b128 v[212:215], v162 offset:56320
	global_load_lds_dwordx4 v[216:217], off
	s_add_i32 m0, s50, 0x2000
	s_add_u32 s48, s48, 0x40080
	v_lshl_add_u64 v[216:217], v[218:219], 0, s[14:15]
	s_addc_u32 s49, s49, 0
	s_add_i32 s50, s88, s55
	global_load_lds_dwordx4 v[216:217], off
	v_lshl_add_u64 v[216:217], s[48:49], 0, v[136:137]
	s_mov_b32 m0, s50
	s_nop 0
	global_load_lds_dwordx4 v[216:217], off
	v_lshl_add_u64 v[216:217], s[48:49], 0, v[140:141]
	s_add_i32 m0, s50, 0x2000
	s_nop 0
	global_load_lds_dwordx4 v[216:217], off
	v_lshl_add_u64 v[216:217], v[220:221], 0, s[14:15]
	s_mov_b32 m0, s64
	s_nop 0
	global_load_lds_dwordx4 v[216:217], off
	v_lshl_add_u64 v[216:217], v[222:223], 0, s[14:15]
	s_mov_b32 m0, s65
	s_nop 0
	global_load_lds_dwordx4 v[216:217], off
	s_cmp_lg_u32 s10, s0
	s_cbranch_scc1 .Lmy_p4_wd_n
	s_cmp_gt_u32 s78, 7
	s_cbranch_scc1 .Lmy_p4_wd_n
	s_waitcnt vmcnt(14)
	s_branch .Lmy_p4_wd_done

.Lmy_p4_wd_done:
	s_waitcnt lgkmcnt(0)
	s_barrier
	s_setprio 1
	s_waitcnt lgkmcnt(0)
	v_mfma_f32_16x16x32_bf16 v[62:65], v[146:149], v[184:187], v[62:65]
	v_mfma_f32_16x16x32_bf16 v[58:61], v[154:157], v[184:187], v[58:61]
	v_mfma_f32_16x16x32_bf16 v[46:49], v[146:149], v[192:195], v[46:49]
	v_mfma_f32_16x16x32_bf16 v[42:45], v[154:157], v[192:195], v[42:45]
	v_mfma_f32_16x16x32_bf16 v[6:9], v[146:149], v[200:203], v[6:9]
	v_mfma_f32_16x16x32_bf16 v[2:5], v[154:157], v[200:203], v[2:5]
	v_mfma_f32_16x16x32_bf16 v[22:25], v[146:149], v[208:211], v[22:25]
	v_mfma_f32_16x16x32_bf16 v[18:21], v[154:157], v[208:211], v[18:21]
	v_mfma_f32_16x16x32_bf16 v[62:65], v[150:153], v[188:191], v[62:65]
	v_mfma_f32_16x16x32_bf16 v[58:61], v[164:167], v[188:191], v[58:61]
	v_mfma_f32_16x16x32_bf16 v[46:49], v[150:153], v[196:199], v[46:49]
	v_mfma_f32_16x16x32_bf16 v[42:45], v[164:167], v[196:199], v[42:45]
	v_mfma_f32_16x16x32_bf16 v[6:9], v[150:153], v[204:207], v[6:9]
	v_mfma_f32_16x16x32_bf16 v[2:5], v[164:167], v[204:207], v[2:5]
	v_mfma_f32_16x16x32_bf16 v[22:25], v[150:153], v[212:215], v[22:25]
	v_mfma_f32_16x16x32_bf16 v[18:21], v[164:167], v[212:215], v[18:21]
	s_setprio 0
	s_setprio 1
	v_mfma_f32_16x16x32_bf16 v[54:57], v[168:171], v[184:187], v[54:57]
	v_mfma_f32_16x16x32_bf16 v[50:53], v[176:179], v[184:187], v[50:53]
	v_mfma_f32_16x16x32_bf16 v[38:41], v[168:171], v[192:195], v[38:41]
	v_mfma_f32_16x16x32_bf16 v[34:37], v[176:179], v[192:195], v[34:37]
	v_mfma_f32_16x16x32_bf16 v[14:17], v[168:171], v[200:203], v[14:17]
	v_mfma_f32_16x16x32_bf16 v[10:13], v[176:179], v[200:203], v[10:13]
	v_mfma_f32_16x16x32_bf16 v[30:33], v[168:171], v[208:211], v[30:33]
	v_mfma_f32_16x16x32_bf16 v[26:29], v[176:179], v[208:211], v[26:29]
	v_mfma_f32_16x16x32_bf16 v[54:57], v[172:175], v[188:191], v[54:57]
	v_mfma_f32_16x16x32_bf16 v[50:53], v[180:183], v[188:191], v[50:53]
	v_mfma_f32_16x16x32_bf16 v[38:41], v[172:175], v[196:199], v[38:41]
	v_mfma_f32_16x16x32_bf16 v[34:37], v[180:183], v[196:199], v[34:37]
	v_mfma_f32_16x16x32_bf16 v[14:17], v[172:175], v[204:207], v[14:17]
	v_mfma_f32_16x16x32_bf16 v[10:13], v[180:183], v[204:207], v[10:13]
	v_mfma_f32_16x16x32_bf16 v[30:33], v[172:175], v[212:215], v[30:33]
	v_mfma_f32_16x16x32_bf16 v[26:29], v[180:183], v[212:215], v[26:29]
	s_setprio 0
	s_barrier
	s_add_i32 s80, s80, 2
	s_add_u32 s81, s81, 0x100
	s_addc_u32 s82, s82, 0
	s_add_u32 s83, s83, 0x100
	s_addc_u32 s84, s84, 0
	s_add_u32 s0, s0, 0xffffff00
	s_addc_u32 s1, s1, -1
	v_lshl_add_u64 v[130:131], v[130:131], 0, s[18:19]
	s_cmp_gt_u32 s80, 13
	v_lshl_add_u64 v[132:133], v[132:133], 0, s[18:19]
	s_cbranch_scc0 .LBB0_689
	s_add_u32 s0, s43, 0x40080
	s_addc_u32 s1, s5, 0
	s_mov_b32 m0, s86
	v_lshl_add_u64 v[130:131], s[0:1], 0, v[134:135]
	global_load_lds_dwordx4 v[130:131], off
	v_lshl_add_u64 v[130:131], s[0:1], 0, v[138:139]
	s_mov_b32 m0, s85
	s_and_b64 vcc, exec, s[16:17]
	global_load_lds_dwordx4 v[130:131], off
	s_cbranch_vccz .LBB0_692
	s_barrier

.LBB0_696:
	s_lshl_b32 s4, s78, 3
	s_and_b32 s4, s4, -16
	s_ashr_i32 s5, s4, 31
	s_lshl_b64 s[4:5], s[4:5], 2
	s_add_u32 s4, s60, s4
	s_addc_u32 s5, s61, s5
	v_ashrrev_i32_e32 v149, 31, v148
	v_lshl_add_u64 v[150:151], v[150:151], 1, s[0:1]
	v_lshlrev_b64 v[130:131], 12, v[146:147]
	v_lshl_add_u64 v[154:155], v[150:151], 0, v[130:131]
	v_lshl_add_u64 v[152:153], v[148:149], 4, s[4:5]
	v_lshlrev_b64 v[130:131], 8, v[146:147]
	v_lshl_add_u64 v[130:131], v[152:153], 0, v[130:131]
	s_waitcnt vmcnt(10)
	v_mov_b32_e32 v164, v226
	v_mov_b32_e32 v165, v227
	v_mov_b32_e32 v166, v228
	v_mov_b32_e32 v167, v229
	v_mov_b32_e32 v168, v230
	v_mov_b32_e32 v169, v231
	v_mov_b32_e32 v170, v232
	v_mov_b32_e32 v171, v233
	v_add_u32_e32 v130, 16, v146
	v_ashrrev_i32_e32 v131, 31, v130
	v_lshlrev_b64 v[132:133], 8, v[130:131]
	v_lshl_add_u64 v[132:133], v[152:153], 0, v[132:133]
	v_mov_b32_e32 v172, v234
	v_mov_b32_e32 v173, v235
	v_mov_b32_e32 v174, v236
	v_mov_b32_e32 v175, v237
	v_mov_b32_e32 v176, v238
	v_mov_b32_e32 v177, v239
	v_mov_b32_e32 v178, v240
	v_mov_b32_e32 v179, v241
	v_mul_f32_e32 v132, 0xbfb8aa3b, v126
	v_mul_f32_e32 v135, 0xbfb8aa3b, v127
	v_mul_f32_e32 v133, 0xbfb8aa3b, v122
	v_mul_f32_e32 v156, 0xbfb8aa3b, v129
	v_mul_f32_e32 v157, 0xbfb8aa3b, v125
	v_exp_f32_e32 v163, v132
	v_exp_f32_e32 v135, v135
	v_lshlrev_b64 v[130:131], 12, v[130:131]
	v_exp_f32_e32 v184, v133
	v_exp_f32_e32 v185, v156
	v_exp_f32_e32 v186, v157
	v_lshl_add_u64 v[156:157], v[150:151], 0, v[130:131]
	v_mov_b32_e32 v180, v242
	v_mov_b32_e32 v181, v243
	v_mov_b32_e32 v182, v244
	v_mov_b32_e32 v183, v245
	v_mov_b32_e32 v130, v246
	v_mov_b32_e32 v131, v247
	v_mov_b32_e32 v132, v248
	v_mov_b32_e32 v133, v249
	v_add_f32_e32 v163, 1.0, v163
	v_add_f32_e32 v135, 1.0, v135
	v_add_f32_e32 v187, 1.0, v184
	v_add_f32_e32 v189, 1.0, v185
	v_rcp_f32_e32 v184, v163
	v_rcp_f32_e32 v185, v135
	v_mul_f32_e32 v137, 0xbfb8aa3b, v123
	v_mul_f32_e32 v147, 0xbfb8aa3b, v124
	v_exp_f32_e32 v137, v137
	v_pk_mul_f32 v[184:185], v[126:127], v[184:185]
	v_exp_f32_e32 v147, v147
	v_mov_b64_e32 v[148:149], s[38:39]
	v_mul_f32_e32 v139, 0xbfb8aa3b, v128
	v_exp_f32_e32 v139, v139
	v_add_f32_e32 v137, 1.0, v137
	v_add_f32_e32 v147, 1.0, v147
	v_add_f32_e32 v191, 1.0, v186
	v_rcp_f32_e32 v186, v187
	v_rcp_f32_e32 v187, v137
	v_rcp_f32_e32 v190, v147
	v_rcp_f32_e32 v191, v191
	v_add_f32_e32 v139, 1.0, v139
	v_rcp_f32_e32 v188, v139
	v_rcp_f32_e32 v189, v189
	v_pk_mul_f32 v[124:125], v[124:125], v[190:191]
	v_pk_mul_f32 v[122:123], v[122:123], v[186:187]
	v_pk_mul_f32 v[128:129], v[128:129], v[188:189]
	s_waitcnt vmcnt(10)
	v_lshlrev_b32_e32 v192, 16, v166
	v_mov_b32_e32 v126, v169
	v_mov_b32_e32 v127, v170
	v_mov_b32_e32 v169, v171
	v_pk_add_f32 v[126:127], v[126:127], v[168:169]
	v_and_b32_e32 v193, 0xffff0000, v166
	v_mov_b32_e32 v170, v173
	v_mov_b32_e32 v171, v174
	v_mov_b32_e32 v173, v175
	v_pk_add_f32 v[168:169], v[170:171], v[172:173]
	v_pk_add_f32 v[126:127], v[126:127], v[126:127] op_sel:[0,1] op_sel_hi:[1,0]
	v_pk_add_f32 v[168:169], v[168:169], v[168:169] op_sel:[0,1] op_sel_hi:[1,0]
	v_mov_b32_e32 v127, v126
	v_mov_b32_e32 v135, v168
	s_nop 0
	v_permlane16_swap_b32_e32 v126, v127
	v_permlane16_swap_b32_e32 v168, v135
	v_add_f32_e32 v127, v126, v127
	v_add_f32_e32 v126, v168, v135
	v_mov_b32_e32 v169, v127
	v_mov_b32_e32 v168, v126
	s_nop 0
	v_permlane32_swap_b32_e32 v127, v169
	v_permlane32_swap_b32_e32 v126, v168
	v_pk_add_f32 v[126:127], v[126:127], v[168:169]
	v_lshlrev_b32_e32 v166, 16, v167
	v_pk_fma_f32 v[126:127], v[126:127], s[36:37], v[148:149] op_sel_hi:[1,0,0]
	v_and_b32_e32 v167, 0xffff0000, v167
	v_mul_f32_e32 v135, 0x4b800000, v127
	v_cmp_gt_f32_e32 vcc, s76, v127
	v_pk_mul_f32 v[122:123], v[122:123], v[192:193]
	v_pk_mul_f32 v[124:125], v[124:125], v[166:167]
	v_cndmask_b32_e32 v127, v127, v135, vcc
	v_rsq_f32_e32 v127, v127
	v_lshlrev_b32_e32 v188, 16, v164
	v_and_b32_e32 v189, 0xffff0000, v164
	v_lshlrev_b32_e32 v164, 16, v165
	v_mul_f32_e32 v135, 0x45800000, v127
	v_cndmask_b32_e32 v168, v127, v135, vcc
	v_and_b32_e32 v165, 0xffff0000, v165
	v_pk_mul_f32 v[166:167], v[124:125], v[168:169] op_sel_hi:[1,0]
	v_pk_mul_f32 v[124:125], v[122:123], v[168:169] op_sel_hi:[1,0]
	v_pk_mul_f32 v[128:129], v[128:129], v[164:165]
	v_cvt_pk_bf16_f32 v124, v124, v125
	v_mul_f32_e32 v125, 0xbfb8aa3b, v118
	v_pk_mul_f32 v[128:129], v[128:129], v[168:169] op_sel_hi:[1,0]
	v_exp_f32_e32 v127, v125
	v_mul_f32_e32 v125, 0xbfb8aa3b, v114
	v_cvt_pk_bf16_f32 v123, v128, v129
	v_exp_f32_e32 v129, v125
	v_add_f32_e32 v127, 1.0, v127
	v_mul_f32_e32 v137, 0x4b800000, v126
	v_cmp_gt_f32_e64 s[4:5], s76, v126
	v_rcp_f32_e32 v128, v127
	v_add_f32_e32 v127, 1.0, v129
	v_mul_f32_e32 v129, 0xbfb8aa3b, v119
	v_cndmask_b32_e64 v126, v126, v137, s[4:5]
	v_exp_f32_e32 v129, v129
	v_mul_f32_e32 v135, 0xbfb8aa3b, v115
	v_rsq_f32_e32 v126, v126
	v_exp_f32_e32 v135, v135
	v_pk_mul_f32 v[170:171], v[184:185], v[188:189]
	v_cvt_pk_bf16_f32 v125, v166, v167
	v_pk_mul_f32 v[164:165], v[170:171], v[168:169] op_sel_hi:[1,0]
	v_mul_f32_e32 v137, 0x45800000, v126
	v_cvt_pk_bf16_f32 v122, v164, v165
	v_rcp_f32_e32 v164, v127
	v_add_f32_e32 v127, 1.0, v129
	v_rcp_f32_e32 v129, v127
	v_add_f32_e32 v127, 1.0, v135
	v_mul_f32_e32 v135, 0xbfb8aa3b, v120
	v_cndmask_b32_e64 v126, v126, v137, s[4:5]
	v_exp_f32_e32 v135, v135
	v_mul_f32_e32 v137, 0xbfb8aa3b, v116
	v_exp_f32_e32 v137, v137
	v_rcp_f32_e32 v165, v127
	v_add_f32_e32 v127, 1.0, v135
	v_mul_f32_e32 v135, 0xbfb8aa3b, v121
	v_rcp_f32_e32 v166, v127
	v_add_f32_e32 v127, 1.0, v137
	v_exp_f32_e32 v135, v135
	v_mul_f32_e32 v137, 0xbfb8aa3b, v117
	v_exp_f32_e32 v137, v137
	v_rcp_f32_e32 v170, v127
	v_add_f32_e32 v127, 1.0, v135
	v_rcp_f32_e32 v167, v127
	v_add_f32_e32 v127, 1.0, v137
	v_rcp_f32_e32 v171, v127
	v_lshlrev_b32_e32 v172, 16, v176
	v_and_b32_e32 v173, 0xffff0000, v176
	v_lshlrev_b32_e32 v174, 16, v177
	v_and_b32_e32 v175, 0xffff0000, v177
	v_lshlrev_b32_e32 v176, 16, v178
	v_and_b32_e32 v177, 0xffff0000, v178
	v_lshlrev_b32_e32 v178, 16, v179
	v_and_b32_e32 v179, 0xffff0000, v179
	v_pk_mul_f32 v[116:117], v[116:117], v[170:171]
	v_pk_mul_f32 v[114:115], v[114:115], v[164:165]
	v_pk_mul_f32 v[118:119], v[118:119], v[128:129]
	v_pk_mul_f32 v[114:115], v[114:115], v[176:177]
	v_pk_mul_f32 v[116:117], v[116:117], v[178:179]
	v_pk_mul_f32 v[120:121], v[120:121], v[166:167]
	v_pk_mul_f32 v[118:119], v[118:119], v[172:173]
	v_pk_mul_f32 v[128:129], v[116:117], v[168:169] op_sel_hi:[1,0]
	v_pk_mul_f32 v[116:117], v[114:115], v[168:169] op_sel_hi:[1,0]
	v_pk_mul_f32 v[120:121], v[120:121], v[174:175]
	v_pk_mul_f32 v[118:119], v[118:119], v[168:169] op_sel_hi:[1,0]
	v_cvt_pk_bf16_f32 v116, v116, v117
	v_mul_f32_e32 v117, 0xbfb8aa3b, v110
	v_pk_mul_f32 v[120:121], v[120:121], v[168:169] op_sel_hi:[1,0]
	v_cvt_pk_bf16_f32 v114, v118, v119
	v_exp_f32_e32 v118, v117
	v_mul_f32_e32 v117, 0xbfb8aa3b, v106
	v_cvt_pk_bf16_f32 v115, v120, v121
	v_exp_f32_e32 v119, v117
	v_mul_f32_e32 v120, 0xbfb8aa3b, v111
	v_mul_f32_e32 v121, 0xbfb8aa3b, v107
	v_exp_f32_e32 v120, v120
	v_exp_f32_e32 v121, v121
	v_add_f32_e32 v119, 1.0, v119
	v_cvt_pk_bf16_f32 v117, v128, v129
	v_rcp_f32_e32 v128, v119
	v_add_f32_e32 v119, 1.0, v120
	v_add_f32_e32 v120, 1.0, v121
	v_mul_f32_e32 v121, 0xbfb8aa3b, v112
	v_mul_f32_e32 v127, 0xbfb8aa3b, v108
	v_exp_f32_e32 v121, v121
	v_exp_f32_e32 v127, v127
	v_rcp_f32_e32 v129, v120
	v_add_f32_e32 v118, 1.0, v118
	v_add_f32_e32 v120, 1.0, v121
	v_add_f32_e32 v121, 1.0, v127
	v_mul_f32_e32 v127, 0xbfb8aa3b, v113
	v_exp_f32_e32 v127, v127
	v_rcp_f32_e32 v164, v121
	v_rcp_f32_e32 v118, v118
	v_rcp_f32_e32 v119, v119
	v_add_f32_e32 v121, 1.0, v127
	v_rcp_f32_e32 v120, v120
	v_rcp_f32_e32 v121, v121
	v_add_u32_e32 v174, 48, v146
	v_add_u32_e32 v176, 32, v146
	v_lshlrev_b32_e32 v166, 16, v180
	v_and_b32_e32 v167, 0xffff0000, v180
	v_lshlrev_b32_e32 v168, 16, v181
	v_and_b32_e32 v169, 0xffff0000, v181
	v_pk_mul_f32 v[112:113], v[112:113], v[120:121]
	v_pk_mul_f32 v[110:111], v[110:111], v[118:119]
	v_ashrrev_i32_e32 v175, 31, v174
	v_ashrrev_i32_e32 v177, 31, v176
	v_pk_mul_f32 v[166:167], v[110:111], v[166:167]
	v_pk_mul_f32 v[168:169], v[112:113], v[168:169]
	v_lshlrev_b64 v[110:111], 8, v[174:175]
	v_lshlrev_b64 v[112:113], 8, v[176:177]
	v_lshl_add_u64 v[110:111], v[152:153], 0, v[110:111]
	v_lshl_add_u64 v[118:119], v[152:153], 0, v[112:113]
	global_load_dwordx4 v[110:113], v[110:111], off
	s_nop 0
	global_load_dwordx4 v[118:121], v[118:119], off
	v_mul_f32_e32 v135, 0xbfb8aa3b, v109
	v_exp_f32_e32 v135, v135
	v_lshlrev_b32_e32 v170, 16, v182
	v_and_b32_e32 v171, 0xffff0000, v182
	v_lshlrev_b32_e32 v172, 16, v183
	v_add_f32_e32 v127, 1.0, v135
	v_rcp_f32_e32 v165, v127
	v_and_b32_e32 v173, 0xffff0000, v183
	v_pk_mul_f32 v[106:107], v[106:107], v[128:129]
	v_pk_mul_f32 v[166:167], v[166:167], v[126:127] op_sel_hi:[1,0]
	v_pk_mul_f32 v[108:109], v[108:109], v[164:165]
	v_pk_mul_f32 v[106:107], v[106:107], v[170:171]
	v_pk_mul_f32 v[108:109], v[108:109], v[172:173]
	v_pk_mul_f32 v[106:107], v[106:107], v[126:127] op_sel_hi:[1,0]
	v_pk_mul_f32 v[108:109], v[108:109], v[126:127] op_sel_hi:[1,0]
	v_cvt_pk_bf16_f32 v164, v166, v167
	v_cvt_pk_bf16_f32 v166, v106, v107
	v_mul_f32_e32 v107, 0xbfb8aa3b, v98
	v_cvt_pk_bf16_f32 v167, v108, v109
	v_mul_f32_e32 v108, 0xbfb8aa3b, v103
	v_exp_f32_e32 v107, v107
	v_exp_f32_e32 v109, v108
	v_mul_f32_e32 v108, 0xbfb8aa3b, v99
	v_pk_mul_f32 v[168:169], v[168:169], v[126:127] op_sel_hi:[1,0]
	v_exp_f32_e32 v127, v108
	v_add_f32_e32 v107, 1.0, v107
	v_rcp_f32_e32 v108, v107
	v_add_f32_e32 v107, 1.0, v109
	v_add_f32_e32 v109, 1.0, v127
	v_mul_f32_e32 v127, 0xbfb8aa3b, v104
	v_exp_f32_e32 v127, v127
	v_mul_f32_e32 v128, 0xbfb8aa3b, v100
	v_exp_f32_e32 v129, v128
	v_mul_f32_e32 v106, 0xbfb8aa3b, v102
	v_add_f32_e32 v127, 1.0, v127
	v_rcp_f32_e32 v128, v127
	v_add_f32_e32 v127, 1.0, v129
	v_mul_f32_e32 v129, 0xbfb8aa3b, v105
	v_exp_f32_e32 v129, v129
	v_mul_f32_e32 v135, 0xbfb8aa3b, v101
	v_exp_f32_e32 v106, v106
	v_exp_f32_e32 v135, v135
	v_rcp_f32_e32 v109, v109
	v_cvt_pk_bf16_f32 v165, v168, v169
	v_rcp_f32_e32 v168, v127
	v_add_f32_e32 v127, 1.0, v129
	v_add_f32_e32 v106, 1.0, v106
	v_rcp_f32_e32 v129, v127
	v_add_f32_e32 v127, 1.0, v135
	v_rcp_f32_e32 v106, v106
	v_rcp_f32_e32 v107, v107
	v_rcp_f32_e32 v169, v127
	v_lshlrev_b32_e32 v172, 16, v132
	v_and_b32_e32 v173, 0xffff0000, v132
	v_pk_mul_f32 v[98:99], v[98:99], v[108:109]
	v_pk_mul_f32 v[104:105], v[104:105], v[128:129]
	v_pk_mul_f32 v[98:99], v[98:99], v[172:173]
	v_lshlrev_b32_e32 v170, 16, v130
	v_pk_mul_f32 v[98:99], v[98:99], v[126:127] op_sel_hi:[1,0]
	v_and_b32_e32 v171, 0xffff0000, v130
	v_cvt_pk_bf16_f32 v128, v98, v99
	v_lshlrev_b64 v[98:99], 12, v[176:177]
	v_lshlrev_b32_e32 v130, 16, v131
	v_and_b32_e32 v131, 0xffff0000, v131
	v_lshlrev_b32_e32 v132, 16, v133
	v_and_b32_e32 v133, 0xffff0000, v133
	v_pk_mul_f32 v[102:103], v[102:103], v[106:107]
	v_pk_mul_f32 v[100:101], v[100:101], v[168:169]
	v_lshl_add_u64 v[108:109], v[150:151], 0, v[98:99]
	v_pk_mul_f32 v[102:103], v[102:103], v[170:171]
	v_pk_mul_f32 v[104:105], v[104:105], v[130:131]
	v_pk_mul_f32 v[100:101], v[100:101], v[132:133]
	global_load_dwordx4 v[130:133], v[108:109], off offset:256
	global_load_dwordx4 v[168:171], v[108:109], off
	v_lshlrev_b64 v[98:99], 12, v[174:175]
	v_pk_mul_f32 v[104:105], v[104:105], v[126:127] op_sel_hi:[1,0]
	v_pk_mul_f32 v[102:103], v[102:103], v[126:127] op_sel_hi:[1,0]
	v_pk_mul_f32 v[100:101], v[100:101], v[126:127] op_sel_hi:[1,0]
	v_lshl_add_u64 v[106:107], v[150:151], 0, v[98:99]
	v_cvt_pk_bf16_f32 v126, v102, v103
	v_cvt_pk_bf16_f32 v127, v104, v105
	v_cvt_pk_bf16_f32 v129, v100, v101
	global_load_dwordx4 v[98:101], v[106:107], off offset:256
	global_load_dwordx4 v[102:105], v[106:107], off
	s_nop 0
	global_store_dwordx4 v[154:155], v[122:125], off
	global_store_dwordx4 v[154:155], v[114:117], off offset:256
	global_store_dwordx4 v[156:157], v[164:167], off
	global_store_dwordx4 v[156:157], v[126:129], off offset:256
	s_waitcnt vmcnt(0)
	v_mov_b32_e32 v114, v119
	v_mov_b32_e32 v115, v120
	v_mov_b32_e32 v119, v121
	v_pk_add_f32 v[114:115], v[114:115], v[118:119]
	v_mov_b32_e32 v118, v111
	v_mov_b32_e32 v119, v112
	v_mov_b32_e32 v111, v113
	v_pk_add_f32 v[110:111], v[118:119], v[110:111]
	v_pk_add_f32 v[114:115], v[114:115], v[114:115] op_sel:[0,1] op_sel_hi:[1,0]
	v_pk_add_f32 v[110:111], v[110:111], v[110:111] op_sel:[0,1] op_sel_hi:[1,0]
	v_mov_b32_e32 v115, v114
	v_mov_b32_e32 v111, v110
	s_nop 0
	v_permlane16_swap_b32_e32 v114, v115
	v_permlane16_swap_b32_e32 v110, v111
	v_add_f32_e32 v115, v114, v115
	v_add_f32_e32 v114, v110, v111
	v_mov_b32_e32 v117, v115
	v_mov_b32_e32 v116, v114
	s_nop 0
	v_permlane32_swap_b32_e32 v115, v117
	v_permlane32_swap_b32_e32 v114, v116
	v_pk_add_f32 v[110:111], v[114:115], v[116:117]
	v_mul_f32_e32 v113, 0xbfb8aa3b, v94
	v_pk_fma_f32 v[110:111], v[110:111], s[36:37], v[148:149] op_sel_hi:[1,0,0]
	v_exp_f32_e32 v113, v113
	v_mul_f32_e32 v112, 0x4b800000, v111
	v_cmp_gt_f32_e32 vcc, s76, v111
	v_cmp_gt_f32_e64 s[4:5], s76, v110
	v_mul_f32_e32 v114, 0xbfb8aa3b, v90
	v_cndmask_b32_e32 v111, v111, v112, vcc
	v_mul_f32_e32 v112, 0x4b800000, v110
	v_rsq_f32_e32 v111, v111
	v_cndmask_b32_e64 v110, v110, v112, s[4:5]
	v_rsq_f32_e32 v110, v110
	v_exp_f32_e32 v115, v114
	v_mul_f32_e32 v112, 0x45800000, v111
	v_cndmask_b32_e32 v112, v111, v112, vcc
	v_mul_f32_e32 v111, 0x45800000, v110
	v_cndmask_b32_e64 v110, v110, v111, s[4:5]
	v_add_f32_e32 v111, 1.0, v113
	v_mul_f32_e32 v113, 0xbfb8aa3b, v95
	v_rcp_f32_e32 v114, v111
	v_add_f32_e32 v111, 1.0, v115
	v_exp_f32_e32 v113, v113
	v_mul_f32_e32 v115, 0xbfb8aa3b, v91
	v_exp_f32_e32 v117, v115
	v_rcp_f32_e32 v116, v111
	v_add_f32_e32 v111, 1.0, v113
	v_mul_f32_e32 v113, 0xbfb8aa3b, v96
	v_rcp_f32_e32 v115, v111
	v_add_f32_e32 v111, 1.0, v117
	v_exp_f32_e32 v113, v113
	v_mul_f32_e32 v117, 0xbfb8aa3b, v92
	v_exp_f32_e32 v119, v117
	v_rcp_f32_e32 v117, v111
	v_add_f32_e32 v111, 1.0, v113
	v_mul_f32_e32 v113, 0xbfb8aa3b, v97
	v_rcp_f32_e32 v118, v111
	v_add_f32_e32 v111, 1.0, v119
	v_exp_f32_e32 v113, v113
	v_mul_f32_e32 v119, 0xbfb8aa3b, v93
	v_exp_f32_e32 v121, v119
	v_rcp_f32_e32 v120, v111
	v_add_f32_e32 v111, 1.0, v113
	v_rcp_f32_e32 v119, v111
	v_add_f32_e32 v111, 1.0, v121
	v_rcp_f32_e32 v121, v111
	v_lshlrev_b32_e32 v126, 16, v170
	v_and_b32_e32 v127, 0xffff0000, v170
	v_lshlrev_b32_e32 v128, 16, v171
	v_and_b32_e32 v129, 0xffff0000, v171
	v_pk_mul_f32 v[92:93], v[92:93], v[120:121]
	v_pk_mul_f32 v[90:91], v[90:91], v[116:117]
	v_lshlrev_b32_e32 v122, 16, v168
	v_and_b32_e32 v123, 0xffff0000, v168
	v_lshlrev_b32_e32 v124, 16, v169
	v_and_b32_e32 v125, 0xffff0000, v169
	v_pk_mul_f32 v[96:97], v[96:97], v[118:119]
	v_pk_mul_f32 v[94:95], v[94:95], v[114:115]
	v_pk_mul_f32 v[90:91], v[90:91], v[126:127]
	v_pk_mul_f32 v[92:93], v[92:93], v[128:129]
	v_pk_mul_f32 v[94:95], v[94:95], v[122:123]
	v_pk_mul_f32 v[96:97], v[96:97], v[124:125]
	v_pk_mul_f32 v[114:115], v[92:93], v[112:113] op_sel_hi:[1,0]
	v_pk_mul_f32 v[92:93], v[90:91], v[112:113] op_sel_hi:[1,0]
	v_pk_mul_f32 v[96:97], v[96:97], v[112:113] op_sel_hi:[1,0]
	v_pk_mul_f32 v[94:95], v[94:95], v[112:113] op_sel_hi:[1,0]
	v_cvt_pk_bf16_f32 v92, v92, v93
	v_mul_f32_e32 v93, 0xbfb8aa3b, v86
	v_cvt_pk_bf16_f32 v90, v94, v95
	v_cvt_pk_bf16_f32 v91, v96, v97
	v_exp_f32_e32 v94, v93
	v_mul_f32_e32 v93, 0xbfb8aa3b, v82
	v_mul_f32_e32 v96, 0xbfb8aa3b, v87
	v_exp_f32_e32 v95, v93
	v_exp_f32_e32 v97, v96
	v_mul_f32_e32 v96, 0xbfb8aa3b, v83
	v_exp_f32_e32 v111, v96
	v_add_f32_e32 v95, 1.0, v95
	v_rcp_f32_e32 v96, v95
	v_add_f32_e32 v95, 1.0, v97
	v_add_f32_e32 v97, 1.0, v111
	v_mul_f32_e32 v111, 0xbfb8aa3b, v88
	v_exp_f32_e32 v111, v111
	v_mul_f32_e32 v113, 0xbfb8aa3b, v84
	v_exp_f32_e32 v113, v113
	v_cvt_pk_bf16_f32 v93, v114, v115
	v_add_f32_e32 v111, 1.0, v111
	v_rcp_f32_e32 v114, v111
	v_add_f32_e32 v111, 1.0, v113
	v_mul_f32_e32 v113, 0xbfb8aa3b, v89
	v_exp_f32_e32 v113, v113
	v_mul_f32_e32 v115, 0xbfb8aa3b, v85
	v_exp_f32_e32 v117, v115
	v_rcp_f32_e32 v116, v111
	v_add_f32_e32 v111, 1.0, v113
	v_rcp_f32_e32 v115, v111
	v_add_f32_e32 v111, 1.0, v117
	v_add_f32_e32 v94, 1.0, v94
	v_rcp_f32_e32 v97, v97
	v_rcp_f32_e32 v117, v111
	v_rcp_f32_e32 v94, v94
	v_rcp_f32_e32 v95, v95
	v_lshlrev_b32_e32 v122, 16, v132
	v_and_b32_e32 v123, 0xffff0000, v132
	v_lshlrev_b32_e32 v124, 16, v133
	v_and_b32_e32 v125, 0xffff0000, v133
	v_pk_mul_f32 v[84:85], v[84:85], v[116:117]
	v_pk_mul_f32 v[82:83], v[82:83], v[96:97]
	v_lshlrev_b32_e32 v118, 16, v130
	v_and_b32_e32 v119, 0xffff0000, v130
	v_pk_mul_f32 v[86:87], v[86:87], v[94:95]
	v_pk_mul_f32 v[82:83], v[82:83], v[122:123]
	v_pk_mul_f32 v[84:85], v[84:85], v[124:125]
	v_lshlrev_b32_e32 v120, 16, v131
	v_and_b32_e32 v121, 0xffff0000, v131
	v_pk_mul_f32 v[88:89], v[88:89], v[114:115]
	v_pk_mul_f32 v[86:87], v[86:87], v[118:119]
	v_pk_mul_f32 v[94:95], v[84:85], v[112:113] op_sel_hi:[1,0]
	v_pk_mul_f32 v[84:85], v[82:83], v[112:113] op_sel_hi:[1,0]
	v_pk_mul_f32 v[88:89], v[88:89], v[120:121]
	v_pk_mul_f32 v[86:87], v[86:87], v[112:113] op_sel_hi:[1,0]
	v_cvt_pk_bf16_f32 v84, v84, v85
	v_mul_f32_e32 v85, 0xbfb8aa3b, v78
	v_pk_mul_f32 v[88:89], v[88:89], v[112:113] op_sel_hi:[1,0]
	v_cvt_pk_bf16_f32 v82, v86, v87
	v_exp_f32_e32 v86, v85
	v_mul_f32_e32 v85, 0xbfb8aa3b, v74
	v_cvt_pk_bf16_f32 v83, v88, v89
	v_exp_f32_e32 v87, v85
	v_mul_f32_e32 v88, 0xbfb8aa3b, v79
	v_mul_f32_e32 v89, 0xbfb8aa3b, v75
	v_exp_f32_e32 v88, v88
	v_exp_f32_e32 v89, v89
	v_add_f32_e32 v87, 1.0, v87
	v_cvt_pk_bf16_f32 v85, v94, v95
	v_rcp_f32_e32 v94, v87
	v_add_f32_e32 v87, 1.0, v88
	v_add_f32_e32 v88, 1.0, v89
	v_mul_f32_e32 v89, 0xbfb8aa3b, v80
	v_mul_f32_e32 v95, 0xbfb8aa3b, v76
	v_exp_f32_e32 v89, v89
	v_exp_f32_e32 v96, v95
	v_rcp_f32_e32 v95, v88
	v_add_f32_e32 v86, 1.0, v86
	v_add_f32_e32 v88, 1.0, v89
	v_add_f32_e32 v89, 1.0, v96
	v_mul_f32_e32 v96, 0xbfb8aa3b, v81
	v_exp_f32_e32 v97, v96
	v_mul_f32_e32 v96, 0xbfb8aa3b, v77
	v_exp_f32_e32 v111, v96
	v_rcp_f32_e32 v96, v89
	v_add_f32_e32 v89, 1.0, v97
	v_rcp_f32_e32 v86, v86
	v_rcp_f32_e32 v87, v87
	v_rcp_f32_e32 v88, v88
	v_rcp_f32_e32 v89, v89
	v_add_u32_e32 v116, 0x90, v146
	v_add_u32_e32 v118, 0x80, v146
	v_lshlrev_b32_e32 v112, 16, v102
	v_and_b32_e32 v113, 0xffff0000, v102
	v_lshlrev_b32_e32 v102, 16, v103
	v_and_b32_e32 v103, 0xffff0000, v103
	v_pk_mul_f32 v[80:81], v[80:81], v[88:89]
	v_pk_mul_f32 v[78:79], v[78:79], v[86:87]
	v_ashrrev_i32_e32 v117, 31, v116
	v_ashrrev_i32_e32 v119, 31, v118
	v_pk_mul_f32 v[112:113], v[78:79], v[112:113]
	v_pk_mul_f32 v[102:103], v[80:81], v[102:103]
	v_lshlrev_b64 v[78:79], 8, v[116:117]
	v_lshlrev_b64 v[80:81], 8, v[118:119]
	v_lshl_add_u64 v[78:79], v[152:153], 0, v[78:79]
	v_lshl_add_u64 v[86:87], v[152:153], 0, v[80:81]
	global_load_dwordx4 v[78:81], v[78:79], off
	s_nop 0
	global_load_dwordx4 v[86:89], v[86:87], off
	v_add_f32_e32 v97, 1.0, v111
	v_rcp_f32_e32 v97, v97
	v_lshlrev_b32_e32 v114, 16, v104
	v_and_b32_e32 v115, 0xffff0000, v104
	v_lshlrev_b32_e32 v104, 16, v105
	v_and_b32_e32 v105, 0xffff0000, v105
	v_pk_mul_f32 v[76:77], v[76:77], v[96:97]
	v_pk_mul_f32 v[74:75], v[74:75], v[94:95]
	v_pk_mul_f32 v[76:77], v[76:77], v[104:105]
	v_pk_mul_f32 v[74:75], v[74:75], v[114:115]
	v_pk_mul_f32 v[76:77], v[76:77], v[110:111] op_sel_hi:[1,0]
	v_pk_mul_f32 v[74:75], v[74:75], v[110:111] op_sel_hi:[1,0]
	v_cvt_pk_bf16_f32 v97, v76, v77
	v_cvt_pk_bf16_f32 v96, v74, v75
	v_mul_f32_e32 v75, 0xbfb8aa3b, v66
	v_mul_f32_e32 v76, 0xbfb8aa3b, v71
	v_pk_mul_f32 v[102:103], v[102:103], v[110:111] op_sel_hi:[1,0]
	v_exp_f32_e32 v75, v75
	v_exp_f32_e32 v77, v76
	v_mul_f32_e32 v76, 0xbfb8aa3b, v67
	v_cvt_pk_bf16_f32 v95, v102, v103
	v_exp_f32_e32 v102, v76
	v_mul_f32_e32 v103, 0xbfb8aa3b, v68
	v_mul_f32_e32 v104, 0xbfb8aa3b, v73
	v_add_f32_e32 v75, 1.0, v75
	v_exp_f32_e32 v103, v103
	v_exp_f32_e32 v105, v104
	v_mul_f32_e32 v104, 0xbfb8aa3b, v69
	v_pk_mul_f32 v[112:113], v[112:113], v[110:111] op_sel_hi:[1,0]
	v_mul_f32_e32 v74, 0xbfb8aa3b, v70
	v_rcp_f32_e32 v76, v75
	v_add_f32_e32 v75, 1.0, v77
	v_add_f32_e32 v77, 1.0, v102
	v_mul_f32_e32 v102, 0xbfb8aa3b, v72
	v_exp_f32_e32 v111, v104
	v_exp_f32_e32 v74, v74
	v_exp_f32_e32 v102, v102
	v_rcp_f32_e32 v77, v77
	v_add_f32_e32 v103, 1.0, v103
	v_rcp_f32_e32 v104, v103
	v_add_f32_e32 v103, 1.0, v105
	v_add_f32_e32 v105, 1.0, v111
	v_add_f32_e32 v74, 1.0, v74
	v_add_f32_e32 v102, 1.0, v102
	v_rcp_f32_e32 v105, v105
	v_rcp_f32_e32 v74, v74
	v_rcp_f32_e32 v75, v75
	v_rcp_f32_e32 v102, v102
	v_rcp_f32_e32 v103, v103
	v_lshlrev_b32_e32 v114, 16, v100
	v_and_b32_e32 v115, 0xffff0000, v100
	v_pk_mul_f32 v[66:67], v[66:67], v[76:77]
	v_lshlrev_b32_e32 v100, 16, v101
	v_pk_mul_f32 v[66:67], v[66:67], v[114:115]
	v_and_b32_e32 v101, 0xffff0000, v101
	v_pk_mul_f32 v[68:69], v[68:69], v[104:105]
	v_pk_mul_f32 v[66:67], v[66:67], v[110:111] op_sel_hi:[1,0]
	v_cvt_pk_bf16_f32 v94, v112, v113
	v_lshlrev_b32_e32 v112, 16, v98
	v_and_b32_e32 v113, 0xffff0000, v98
	v_lshlrev_b32_e32 v98, 16, v99
	v_and_b32_e32 v99, 0xffff0000, v99
	v_pk_mul_f32 v[72:73], v[72:73], v[102:103]
	v_pk_mul_f32 v[70:71], v[70:71], v[74:75]
	v_pk_mul_f32 v[68:69], v[68:69], v[100:101]
	v_cvt_pk_bf16_f32 v100, v66, v67
	v_lshlrev_b64 v[66:67], 12, v[118:119]
	v_pk_mul_f32 v[70:71], v[70:71], v[112:113]
	v_pk_mul_f32 v[72:73], v[72:73], v[98:99]
	v_lshl_add_u64 v[74:75], v[150:151], 0, v[66:67]
	v_pk_mul_f32 v[72:73], v[72:73], v[110:111] op_sel_hi:[1,0]
	v_pk_mul_f32 v[70:71], v[70:71], v[110:111] op_sel_hi:[1,0]
	v_pk_mul_f32 v[68:69], v[68:69], v[110:111] op_sel_hi:[1,0]
	global_load_dwordx4 v[102:105], v[74:75], off offset:256
	global_load_dwordx4 v[110:113], v[74:75], off
	v_lshlrev_b64 v[66:67], 12, v[116:117]
	v_lshl_add_u64 v[76:77], v[150:151], 0, v[66:67]
	v_cvt_pk_bf16_f32 v98, v70, v71
	v_cvt_pk_bf16_f32 v99, v72, v73
	v_cvt_pk_bf16_f32 v101, v68, v69
	global_load_dwordx4 v[66:69], v[76:77], off offset:256
	global_load_dwordx4 v[70:73], v[76:77], off
	s_nop 0
	global_store_dwordx4 v[108:109], v[90:93], off
	global_store_dwordx4 v[108:109], v[82:85], off offset:256
	global_store_dwordx4 v[106:107], v[94:97], off
	global_store_dwordx4 v[106:107], v[98:101], off offset:256
	s_waitcnt vmcnt(0)
	v_mov_b32_e32 v82, v87
	v_mov_b32_e32 v83, v88
	v_mov_b32_e32 v87, v89
	v_pk_add_f32 v[82:83], v[82:83], v[86:87]
	v_mov_b32_e32 v86, v79
	v_mov_b32_e32 v87, v80
	v_mov_b32_e32 v79, v81
	v_pk_add_f32 v[78:79], v[86:87], v[78:79]
	v_pk_add_f32 v[82:83], v[82:83], v[82:83] op_sel:[0,1] op_sel_hi:[1,0]
	v_pk_add_f32 v[78:79], v[78:79], v[78:79] op_sel:[0,1] op_sel_hi:[1,0]
	v_mov_b32_e32 v83, v82
	v_mov_b32_e32 v79, v78
	s_nop 0
	v_permlane16_swap_b32_e32 v82, v83
	v_permlane16_swap_b32_e32 v78, v79
	v_add_f32_e32 v83, v82, v83
	v_add_f32_e32 v82, v78, v79
	v_mov_b32_e32 v85, v83
	v_mov_b32_e32 v84, v82
	s_nop 0
	v_permlane32_swap_b32_e32 v83, v85
	v_permlane32_swap_b32_e32 v82, v84
	v_pk_add_f32 v[78:79], v[82:83], v[84:85]
	v_mul_f32_e32 v81, 0xbfb8aa3b, v62
	v_pk_fma_f32 v[78:79], v[78:79], s[36:37], v[148:149] op_sel_hi:[1,0,0]
	v_exp_f32_e32 v81, v81
	v_mul_f32_e32 v80, 0x4b800000, v79
	v_cmp_gt_f32_e32 vcc, s76, v79
	v_cmp_gt_f32_e64 s[4:5], s76, v78
	v_mul_f32_e32 v82, 0xbfb8aa3b, v58
	v_cndmask_b32_e32 v79, v79, v80, vcc
	v_mul_f32_e32 v80, 0x4b800000, v78
	v_rsq_f32_e32 v79, v79
	v_cndmask_b32_e64 v78, v78, v80, s[4:5]
	v_rsq_f32_e32 v78, v78
	v_exp_f32_e32 v83, v82
	v_mul_f32_e32 v80, 0x45800000, v79
	v_cndmask_b32_e32 v80, v79, v80, vcc
	v_mul_f32_e32 v79, 0x45800000, v78
	v_cndmask_b32_e64 v78, v78, v79, s[4:5]
	v_add_f32_e32 v79, 1.0, v81
	v_mul_f32_e32 v81, 0xbfb8aa3b, v63
	v_rcp_f32_e32 v82, v79
	v_add_f32_e32 v79, 1.0, v83
	v_exp_f32_e32 v81, v81
	v_mul_f32_e32 v83, 0xbfb8aa3b, v59
	v_exp_f32_e32 v85, v83
	v_rcp_f32_e32 v84, v79
	v_add_f32_e32 v79, 1.0, v81
	v_mul_f32_e32 v81, 0xbfb8aa3b, v64
	v_rcp_f32_e32 v83, v79
	v_add_f32_e32 v79, 1.0, v85
	v_exp_f32_e32 v81, v81
	v_mul_f32_e32 v85, 0xbfb8aa3b, v60
	v_exp_f32_e32 v87, v85
	v_rcp_f32_e32 v85, v79
	v_add_f32_e32 v79, 1.0, v81
	v_mul_f32_e32 v81, 0xbfb8aa3b, v65
	v_rcp_f32_e32 v86, v79
	v_add_f32_e32 v79, 1.0, v87
	v_exp_f32_e32 v81, v81
	v_mul_f32_e32 v87, 0xbfb8aa3b, v61
	v_exp_f32_e32 v89, v87
	v_rcp_f32_e32 v88, v79
	v_add_f32_e32 v79, 1.0, v81
	v_rcp_f32_e32 v87, v79
	v_add_f32_e32 v79, 1.0, v89
	v_rcp_f32_e32 v89, v79
	v_pk_mul_f32 v[58:59], v[58:59], v[84:85]
	v_lshlrev_b32_e32 v94, 16, v112
	v_and_b32_e32 v95, 0xffff0000, v112
	v_lshlrev_b32_e32 v96, 16, v113
	v_and_b32_e32 v97, 0xffff0000, v113
	v_pk_mul_f32 v[60:61], v[60:61], v[88:89]
	v_lshlrev_b32_e32 v90, 16, v110
	v_and_b32_e32 v91, 0xffff0000, v110
	v_lshlrev_b32_e32 v92, 16, v111
	v_and_b32_e32 v93, 0xffff0000, v111
	v_pk_mul_f32 v[64:65], v[64:65], v[86:87]
	v_pk_mul_f32 v[62:63], v[62:63], v[82:83]
	v_pk_mul_f32 v[58:59], v[58:59], v[94:95]
	v_pk_mul_f32 v[60:61], v[60:61], v[96:97]
	v_pk_mul_f32 v[62:63], v[62:63], v[90:91]
	v_pk_mul_f32 v[64:65], v[64:65], v[92:93]
	v_pk_mul_f32 v[82:83], v[60:61], v[80:81] op_sel_hi:[1,0]
	v_pk_mul_f32 v[60:61], v[58:59], v[80:81] op_sel_hi:[1,0]
	v_pk_mul_f32 v[64:65], v[64:65], v[80:81] op_sel_hi:[1,0]
	v_pk_mul_f32 v[62:63], v[62:63], v[80:81] op_sel_hi:[1,0]
	v_cvt_pk_bf16_f32 v60, v60, v61
	v_mul_f32_e32 v61, 0xbfb8aa3b, v54
	v_cvt_pk_bf16_f32 v58, v62, v63
	v_cvt_pk_bf16_f32 v59, v64, v65
	v_exp_f32_e32 v62, v61
	v_mul_f32_e32 v61, 0xbfb8aa3b, v50
	v_mul_f32_e32 v64, 0xbfb8aa3b, v55
	v_exp_f32_e32 v63, v61
	v_exp_f32_e32 v65, v64
	v_mul_f32_e32 v64, 0xbfb8aa3b, v51
	v_exp_f32_e32 v79, v64
	v_add_f32_e32 v63, 1.0, v63
	v_rcp_f32_e32 v64, v63
	v_add_f32_e32 v63, 1.0, v65
	v_add_f32_e32 v65, 1.0, v79
	v_mul_f32_e32 v79, 0xbfb8aa3b, v56
	v_exp_f32_e32 v79, v79
	v_mul_f32_e32 v81, 0xbfb8aa3b, v52
	v_exp_f32_e32 v81, v81
	v_cvt_pk_bf16_f32 v61, v82, v83
	v_add_f32_e32 v79, 1.0, v79
	v_rcp_f32_e32 v82, v79
	v_add_f32_e32 v79, 1.0, v81
	v_mul_f32_e32 v81, 0xbfb8aa3b, v57
	v_exp_f32_e32 v81, v81
	v_mul_f32_e32 v83, 0xbfb8aa3b, v53
	v_exp_f32_e32 v85, v83
	v_rcp_f32_e32 v84, v79
	v_add_f32_e32 v79, 1.0, v81
	v_rcp_f32_e32 v83, v79
	v_add_f32_e32 v79, 1.0, v85
	v_add_f32_e32 v62, 1.0, v62
	v_rcp_f32_e32 v65, v65
	v_rcp_f32_e32 v85, v79
	v_rcp_f32_e32 v62, v62
	v_rcp_f32_e32 v63, v63
	v_lshlrev_b32_e32 v90, 16, v104
	v_and_b32_e32 v91, 0xffff0000, v104
	v_lshlrev_b32_e32 v92, 16, v105
	v_and_b32_e32 v93, 0xffff0000, v105
	v_pk_mul_f32 v[52:53], v[52:53], v[84:85]
	v_pk_mul_f32 v[50:51], v[50:51], v[64:65]
	v_lshlrev_b32_e32 v86, 16, v102
	v_and_b32_e32 v87, 0xffff0000, v102
	v_pk_mul_f32 v[54:55], v[54:55], v[62:63]
	v_pk_mul_f32 v[50:51], v[50:51], v[90:91]
	v_pk_mul_f32 v[52:53], v[52:53], v[92:93]
	v_lshlrev_b32_e32 v88, 16, v103
	v_and_b32_e32 v89, 0xffff0000, v103
	v_pk_mul_f32 v[56:57], v[56:57], v[82:83]
	v_pk_mul_f32 v[54:55], v[54:55], v[86:87]
	v_pk_mul_f32 v[62:63], v[52:53], v[80:81] op_sel_hi:[1,0]
	v_pk_mul_f32 v[52:53], v[50:51], v[80:81] op_sel_hi:[1,0]
	v_pk_mul_f32 v[56:57], v[56:57], v[88:89]
	v_pk_mul_f32 v[54:55], v[54:55], v[80:81] op_sel_hi:[1,0]
	v_cvt_pk_bf16_f32 v52, v52, v53
	v_mul_f32_e32 v53, 0xbfb8aa3b, v46
	v_pk_mul_f32 v[56:57], v[56:57], v[80:81] op_sel_hi:[1,0]
	v_cvt_pk_bf16_f32 v50, v54, v55
	v_exp_f32_e32 v54, v53
	v_mul_f32_e32 v53, 0xbfb8aa3b, v42
	v_cvt_pk_bf16_f32 v51, v56, v57
	v_exp_f32_e32 v55, v53
	v_mul_f32_e32 v56, 0xbfb8aa3b, v47
	v_mul_f32_e32 v57, 0xbfb8aa3b, v43
	v_exp_f32_e32 v56, v56
	v_exp_f32_e32 v57, v57
	v_add_f32_e32 v55, 1.0, v55
	v_cvt_pk_bf16_f32 v53, v62, v63
	v_rcp_f32_e32 v62, v55
	v_add_f32_e32 v55, 1.0, v56
	v_add_f32_e32 v56, 1.0, v57
	v_mul_f32_e32 v57, 0xbfb8aa3b, v48
	v_mul_f32_e32 v63, 0xbfb8aa3b, v44
	v_exp_f32_e32 v57, v57
	v_exp_f32_e32 v64, v63
	v_rcp_f32_e32 v63, v56
	v_add_f32_e32 v54, 1.0, v54
	v_add_f32_e32 v56, 1.0, v57
	v_add_f32_e32 v57, 1.0, v64
	v_mul_f32_e32 v64, 0xbfb8aa3b, v49
	v_exp_f32_e32 v65, v64
	v_mul_f32_e32 v64, 0xbfb8aa3b, v45
	v_exp_f32_e32 v79, v64
	v_rcp_f32_e32 v64, v57
	v_add_f32_e32 v57, 1.0, v65
	v_rcp_f32_e32 v54, v54
	v_rcp_f32_e32 v55, v55
	v_rcp_f32_e32 v56, v56
	v_rcp_f32_e32 v57, v57
	v_lshlrev_b32_e32 v80, 16, v70
	v_and_b32_e32 v81, 0xffff0000, v70
	v_lshlrev_b32_e32 v70, 16, v71
	v_and_b32_e32 v71, 0xffff0000, v71
	v_pk_mul_f32 v[48:49], v[48:49], v[56:57]
	v_pk_mul_f32 v[46:47], v[46:47], v[54:55]
	v_add_u32_e32 v84, 0xb0, v146
	v_add_u32_e32 v86, 0xa0, v146
	v_pk_mul_f32 v[80:81], v[46:47], v[80:81]
	v_pk_mul_f32 v[46:47], v[48:49], v[70:71]
	v_ashrrev_i32_e32 v85, 31, v84
	v_ashrrev_i32_e32 v87, 31, v86
	v_pk_mul_f32 v[70:71], v[46:47], v[78:79] op_sel_hi:[1,0]
	v_lshlrev_b64 v[46:47], 8, v[84:85]
	v_lshlrev_b64 v[48:49], 8, v[86:87]
	v_lshl_add_u64 v[46:47], v[152:153], 0, v[46:47]
	v_lshl_add_u64 v[54:55], v[152:153], 0, v[48:49]
	global_load_dwordx4 v[46:49], v[46:47], off
	s_nop 0
	global_load_dwordx4 v[54:57], v[54:55], off
	v_add_f32_e32 v65, 1.0, v79
	v_rcp_f32_e32 v65, v65
	v_lshlrev_b32_e32 v82, 16, v72
	v_and_b32_e32 v83, 0xffff0000, v72
	v_lshlrev_b32_e32 v72, 16, v73
	v_and_b32_e32 v73, 0xffff0000, v73
	v_pk_mul_f32 v[44:45], v[44:45], v[64:65]
	v_pk_mul_f32 v[42:43], v[42:43], v[62:63]
	v_pk_mul_f32 v[44:45], v[44:45], v[72:73]
	v_pk_mul_f32 v[42:43], v[42:43], v[82:83]
	v_pk_mul_f32 v[44:45], v[44:45], v[78:79] op_sel_hi:[1,0]
	v_pk_mul_f32 v[42:43], v[42:43], v[78:79] op_sel_hi:[1,0]
	v_cvt_pk_bf16_f32 v65, v44, v45
	v_cvt_pk_bf16_f32 v64, v42, v43
	v_mul_f32_e32 v43, 0xbfb8aa3b, v34
	v_mul_f32_e32 v44, 0xbfb8aa3b, v39
	v_exp_f32_e32 v43, v43
	v_exp_f32_e32 v45, v44
	v_mul_f32_e32 v44, 0xbfb8aa3b, v35
	v_cvt_pk_bf16_f32 v63, v70, v71
	v_exp_f32_e32 v70, v44
	v_add_f32_e32 v43, 1.0, v43
	v_rcp_f32_e32 v44, v43
	v_add_f32_e32 v43, 1.0, v45
	v_add_f32_e32 v45, 1.0, v70
	v_mul_f32_e32 v70, 0xbfb8aa3b, v40
	v_exp_f32_e32 v70, v70
	v_mul_f32_e32 v71, 0xbfb8aa3b, v36
	v_exp_f32_e32 v71, v71
	v_pk_mul_f32 v[80:81], v[80:81], v[78:79] op_sel_hi:[1,0]
	v_add_f32_e32 v70, 1.0, v70
	v_cvt_pk_bf16_f32 v62, v80, v81
	v_rcp_f32_e32 v80, v70
	v_add_f32_e32 v70, 1.0, v71
	v_rcp_f32_e32 v82, v70
	v_mul_f32_e32 v70, 0xbfb8aa3b, v41
	v_exp_f32_e32 v79, v70
	v_mul_f32_e32 v70, 0xbfb8aa3b, v37
	v_exp_f32_e32 v83, v70
	v_lshlrev_b64 v[70:71], 12, v[84:85]
	v_lshl_add_u64 v[152:153], v[150:151], 0, v[70:71]
	global_load_dwordx4 v[70:73], v[152:153], off offset:256
	v_mul_f32_e32 v42, 0xbfb8aa3b, v38
	v_exp_f32_e32 v42, v42
	v_add_f32_e32 v79, 1.0, v79
	v_rcp_f32_e32 v81, v79
	v_add_f32_e32 v79, 1.0, v83
	v_add_f32_e32 v42, 1.0, v42
	v_rcp_f32_e32 v42, v42
	v_rcp_f32_e32 v43, v43
	v_rcp_f32_e32 v45, v45
	v_rcp_f32_e32 v83, v79
	v_lshlrev_b32_e32 v84, 16, v66
	v_and_b32_e32 v85, 0xffff0000, v66
	v_lshlrev_b32_e32 v66, 16, v67
	v_and_b32_e32 v67, 0xffff0000, v67
	v_lshlrev_b32_e32 v88, 16, v68
	v_and_b32_e32 v89, 0xffff0000, v68
	v_lshlrev_b32_e32 v68, 16, v69
	v_and_b32_e32 v69, 0xffff0000, v69
	v_pk_mul_f32 v[40:41], v[40:41], v[80:81]
	v_pk_mul_f32 v[38:39], v[38:39], v[42:43]
	v_pk_mul_f32 v[36:37], v[36:37], v[82:83]
	v_pk_mul_f32 v[34:35], v[34:35], v[44:45]
	v_pk_mul_f32 v[38:39], v[38:39], v[84:85]
	v_pk_mul_f32 v[40:41], v[40:41], v[66:67]
	v_pk_mul_f32 v[34:35], v[34:35], v[88:89]
	v_pk_mul_f32 v[36:37], v[36:37], v[68:69]
	v_pk_mul_f32 v[40:41], v[40:41], v[78:79] op_sel_hi:[1,0]
	v_pk_mul_f32 v[38:39], v[38:39], v[78:79] op_sel_hi:[1,0]
	v_pk_mul_f32 v[36:37], v[36:37], v[78:79] op_sel_hi:[1,0]
	v_pk_mul_f32 v[34:35], v[34:35], v[78:79] op_sel_hi:[1,0]
	global_load_dwordx4 v[78:81], v[152:153], off
	v_cvt_pk_bf16_f32 v68, v34, v35
	v_lshlrev_b64 v[34:35], 12, v[86:87]
	v_lshl_add_u64 v[42:43], v[150:151], 0, v[34:35]
	v_cvt_pk_bf16_f32 v66, v38, v39
	v_cvt_pk_bf16_f32 v67, v40, v41
	v_cvt_pk_bf16_f32 v69, v36, v37
	global_load_dwordx4 v[38:41], v[42:43], off offset:256
	global_load_dwordx4 v[34:37], v[42:43], off
	s_nop 0
	global_store_dwordx4 v[74:75], v[58:61], off
	global_store_dwordx4 v[74:75], v[50:53], off offset:256
	global_store_dwordx4 v[76:77], v[62:65], off
	global_store_dwordx4 v[76:77], v[66:69], off offset:256
	s_waitcnt vmcnt(0)
	v_mov_b32_e32 v52, v47
	v_mov_b32_e32 v53, v48
	v_mov_b32_e32 v47, v49
	v_mov_b32_e32 v44, v55
	v_mov_b32_e32 v45, v56
	v_mov_b32_e32 v55, v57
	v_pk_add_f32 v[46:47], v[52:53], v[46:47]
	v_pk_add_f32 v[44:45], v[44:45], v[54:55]
	v_pk_add_f32 v[46:47], v[46:47], v[46:47] op_sel:[0,1] op_sel_hi:[1,0]
	v_pk_add_f32 v[44:45], v[44:45], v[44:45] op_sel:[0,1] op_sel_hi:[1,0]
	v_mul_f32_e32 v47, 0xbfb8aa3b, v30
	v_mov_b32_e32 v45, v44
	v_exp_f32_e32 v47, v47
	s_nop 0
	v_permlane16_swap_b32_e32 v44, v45
	v_add_f32_e32 v44, v44, v45
	v_mov_b32_e32 v45, v46
	s_nop 1
	v_permlane16_swap_b32_e32 v46, v45
	v_add_f32_e32 v45, v46, v45
	v_add_f32_e32 v46, 1.0, v47
	v_mul_f32_e32 v47, 0xbfb8aa3b, v31
	v_exp_f32_e32 v47, v47
	v_rcp_f32_e32 v46, v46
	v_mul_f32_e32 v53, 0xbfb8aa3b, v27
	v_exp_f32_e32 v53, v53
	v_add_f32_e32 v47, 1.0, v47
	v_rcp_f32_e32 v47, v47
	v_mul_f32_e32 v54, 0xbfb8aa3b, v28
	v_mul_f32_e32 v55, 0xbfb8aa3b, v29
	v_exp_f32_e32 v54, v54
	v_pk_mul_f32 v[30:31], v[30:31], v[46:47]
	v_mul_f32_e32 v47, 0xbfb8aa3b, v26
	v_exp_f32_e32 v52, v47
	v_exp_f32_e32 v55, v55
	v_add_f32_e32 v53, 1.0, v53
	v_add_f32_e32 v54, 1.0, v54
	v_add_f32_e32 v52, 1.0, v52
	v_rcp_f32_e32 v52, v52
	v_add_f32_e32 v55, 1.0, v55
	v_rcp_f32_e32 v53, v53
	v_rcp_f32_e32 v54, v54
	v_rcp_f32_e32 v55, v55
	v_lshlrev_b32_e32 v46, 16, v70
	v_and_b32_e32 v47, 0xffff0000, v70
	v_pk_mul_f32 v[30:31], v[30:31], v[46:47]
	v_pk_mul_f32 v[26:27], v[26:27], v[52:53]
	v_mul_f32_e32 v47, 0xbfb8aa3b, v22
	v_mul_f32_e32 v53, 0xbfb8aa3b, v23
	v_pk_mul_f32 v[28:29], v[28:29], v[54:55]
	v_exp_f32_e32 v52, v47
	v_exp_f32_e32 v53, v53
	v_mul_f32_e32 v54, 0xbfb8aa3b, v24
	v_mul_f32_e32 v55, 0xbfb8aa3b, v25
	v_mul_f32_e32 v48, 0xbfb8aa3b, v32
	v_mul_f32_e32 v49, 0xbfb8aa3b, v33
	v_exp_f32_e32 v54, v54
	v_exp_f32_e32 v55, v55
	v_exp_f32_e32 v48, v48
	v_exp_f32_e32 v49, v49
	v_add_f32_e32 v52, 1.0, v52
	v_add_f32_e32 v53, 1.0, v53
	v_rcp_f32_e32 v52, v52
	v_add_f32_e32 v54, 1.0, v54
	v_add_f32_e32 v55, 1.0, v55
	v_rcp_f32_e32 v53, v53
	v_add_f32_e32 v48, 1.0, v48
	v_add_f32_e32 v49, 1.0, v49
	v_rcp_f32_e32 v54, v54
	v_rcp_f32_e32 v55, v55
	v_rcp_f32_e32 v48, v48
	v_rcp_f32_e32 v49, v49
	v_lshlrev_b32_e32 v46, 16, v72
	v_and_b32_e32 v47, 0xffff0000, v72
	v_pk_mul_f32 v[26:27], v[26:27], v[46:47]
	v_pk_mul_f32 v[22:23], v[22:23], v[52:53]
	v_mul_f32_e32 v47, 0xbfb8aa3b, v18
	v_mul_f32_e32 v53, 0xbfb8aa3b, v19
	v_mov_b32_e32 v50, v44
	v_mov_b32_e32 v51, v45
	v_pk_mul_f32 v[24:25], v[24:25], v[54:55]
	v_exp_f32_e32 v52, v47
	v_exp_f32_e32 v53, v53
	v_mul_f32_e32 v54, 0xbfb8aa3b, v20
	v_mul_f32_e32 v55, 0xbfb8aa3b, v21
	v_permlane32_swap_b32_e32 v44, v50
	v_permlane32_swap_b32_e32 v45, v51
	v_pk_mul_f32 v[32:33], v[32:33], v[48:49]
	v_lshlrev_b32_e32 v48, 16, v71
	v_and_b32_e32 v49, 0xffff0000, v71
	v_exp_f32_e32 v54, v54
	v_exp_f32_e32 v55, v55
	v_pk_mul_f32 v[32:33], v[32:33], v[48:49]
	v_lshlrev_b32_e32 v48, 16, v73
	v_and_b32_e32 v49, 0xffff0000, v73
	v_pk_add_f32 v[44:45], v[44:45], v[50:51]
	v_pk_mul_f32 v[28:29], v[28:29], v[48:49]
	v_lshlrev_b32_e32 v48, 16, v79
	v_and_b32_e32 v49, 0xffff0000, v79
	v_pk_fma_f32 v[44:45], v[44:45], s[36:37], v[148:149] op_sel_hi:[1,0,0]
	v_add_f32_e32 v52, 1.0, v52
	v_add_f32_e32 v53, 1.0, v53
	v_pk_mul_f32 v[24:25], v[24:25], v[48:49]
	v_mul_f32_e32 v49, 0x4b800000, v45
	v_cmp_gt_f32_e32 vcc, s76, v45
	v_rcp_f32_e32 v52, v52
	v_add_f32_e32 v54, 1.0, v54
	v_add_f32_e32 v55, 1.0, v55
	v_rcp_f32_e32 v53, v53
	v_cndmask_b32_e32 v45, v45, v49, vcc
	v_rcp_f32_e32 v54, v54
	v_rcp_f32_e32 v55, v55
	v_rsq_f32_e32 v45, v45
	v_lshlrev_b32_e32 v46, 16, v78
	v_and_b32_e32 v47, 0xffff0000, v78
	v_pk_mul_f32 v[22:23], v[22:23], v[46:47]
	v_pk_mul_f32 v[18:19], v[18:19], v[52:53]
	v_lshlrev_b32_e32 v46, 16, v80
	v_and_b32_e32 v47, 0xffff0000, v80
	v_pk_mul_f32 v[20:21], v[20:21], v[54:55]
	v_lshlrev_b32_e32 v48, 16, v81
	v_and_b32_e32 v49, 0xffff0000, v81
	v_pk_mul_f32 v[46:47], v[18:19], v[46:47]
	v_mul_f32_e32 v18, 0x45800000, v45
	v_pk_mul_f32 v[20:21], v[20:21], v[48:49]
	v_cndmask_b32_e32 v48, v45, v18, vcc
	v_pk_mul_f32 v[18:19], v[32:33], v[48:49] op_sel_hi:[1,0]
	v_cmp_gt_f32_e32 vcc, s76, v44
	v_cvt_pk_bf16_f32 v131, v18, v19
	v_pk_mul_f32 v[18:19], v[28:29], v[48:49] op_sel_hi:[1,0]
	v_pk_mul_f32 v[26:27], v[26:27], v[48:49] op_sel_hi:[1,0]
	v_cvt_pk_bf16_f32 v133, v18, v19
	v_pk_mul_f32 v[18:19], v[22:23], v[48:49] op_sel_hi:[1,0]
	v_pk_mul_f32 v[22:23], v[20:21], v[48:49] op_sel_hi:[1,0]
	v_pk_mul_f32 v[20:21], v[46:47], v[48:49] op_sel_hi:[1,0]
	v_cvt_pk_bf16_f32 v132, v26, v27
	v_cvt_pk_bf16_f32 v20, v20, v21
	v_cvt_pk_bf16_f32 v21, v22, v23
	v_mul_f32_e32 v23, 0xbfb8aa3b, v14
	v_exp_f32_e32 v23, v23
	v_mul_f32_e32 v22, 0x4b800000, v44
	v_cndmask_b32_e32 v22, v44, v22, vcc
	v_rsq_f32_e32 v26, v22
	v_add_f32_e32 v22, 1.0, v23
	v_mul_f32_e32 v23, 0xbfb8aa3b, v15
	v_exp_f32_e32 v23, v23
	v_pk_mul_f32 v[24:25], v[24:25], v[48:49] op_sel_hi:[1,0]
	v_cvt_pk_bf16_f32 v18, v18, v19
	v_cvt_pk_bf16_f32 v19, v24, v25
	v_add_f32_e32 v23, 1.0, v23
	v_rcp_f32_e32 v22, v22
	v_mul_f32_e32 v24, 0xbfb8aa3b, v16
	v_mul_f32_e32 v25, 0xbfb8aa3b, v17
	v_rcp_f32_e32 v23, v23
	v_exp_f32_e32 v24, v24
	v_exp_f32_e32 v25, v25
	v_mul_f32_e32 v27, 0x45800000, v26
	v_pk_mul_f32 v[14:15], v[14:15], v[22:23]
	v_lshlrev_b32_e32 v22, 16, v38
	v_and_b32_e32 v23, 0xffff0000, v38
	v_add_f32_e32 v24, 1.0, v24
	v_add_f32_e32 v25, 1.0, v25
	v_pk_mul_f32 v[14:15], v[14:15], v[22:23]
	v_mul_f32_e32 v22, 0xbfb8aa3b, v10
	v_mul_f32_e32 v23, 0xbfb8aa3b, v11
	v_rcp_f32_e32 v24, v24
	v_rcp_f32_e32 v25, v25
	v_exp_f32_e32 v22, v22
	v_exp_f32_e32 v23, v23
	v_cndmask_b32_e32 v26, v26, v27, vcc
	v_pk_mul_f32 v[16:17], v[16:17], v[24:25]
	v_lshlrev_b32_e32 v24, 16, v39
	v_and_b32_e32 v25, 0xffff0000, v39
	v_add_f32_e32 v22, 1.0, v22
	v_add_f32_e32 v23, 1.0, v23
	v_pk_mul_f32 v[16:17], v[16:17], v[24:25]
	v_rcp_f32_e32 v22, v22
	v_mul_f32_e32 v24, 0xbfb8aa3b, v12
	v_mul_f32_e32 v25, 0xbfb8aa3b, v13
	v_rcp_f32_e32 v23, v23
	v_exp_f32_e32 v24, v24
	v_exp_f32_e32 v25, v25
	v_pk_mul_f32 v[16:17], v[16:17], v[26:27] op_sel_hi:[1,0]
	v_pk_mul_f32 v[14:15], v[14:15], v[26:27] op_sel_hi:[1,0]
	v_pk_mul_f32 v[10:11], v[10:11], v[22:23]
	v_cvt_pk_bf16_f32 v14, v14, v15
	v_cvt_pk_bf16_f32 v15, v16, v17
	v_lshlrev_b32_e32 v16, 16, v40
	v_and_b32_e32 v17, 0xffff0000, v40
	v_add_f32_e32 v24, 1.0, v24
	v_add_f32_e32 v25, 1.0, v25
	v_pk_mul_f32 v[10:11], v[10:11], v[16:17]
	v_mul_f32_e32 v16, 0xbfb8aa3b, v6
	v_rcp_f32_e32 v24, v24
	v_rcp_f32_e32 v25, v25
	v_exp_f32_e32 v16, v16
	v_lshlrev_b32_e32 v22, 16, v41
	v_and_b32_e32 v23, 0xffff0000, v41
	v_pk_mul_f32 v[12:13], v[12:13], v[24:25]
	v_add_f32_e32 v16, 1.0, v16
	v_mul_f32_e32 v17, 0xbfb8aa3b, v8
	v_pk_mul_f32 v[12:13], v[12:13], v[22:23]
	v_rcp_f32_e32 v22, v16
	v_mul_f32_e32 v16, 0xbfb8aa3b, v7
	v_exp_f32_e32 v17, v17
	v_mul_f32_e32 v23, 0xbfb8aa3b, v9
	v_exp_f32_e32 v16, v16
	v_exp_f32_e32 v23, v23
	v_add_f32_e32 v17, 1.0, v17
	v_rcp_f32_e32 v24, v17
	v_add_f32_e32 v16, 1.0, v16
	v_add_f32_e32 v17, 1.0, v23
	v_rcp_f32_e32 v25, v17
	v_rcp_f32_e32 v23, v16
	v_pk_mul_f32 v[12:13], v[12:13], v[26:27] op_sel_hi:[1,0]
	v_pk_mul_f32 v[10:11], v[10:11], v[26:27] op_sel_hi:[1,0]
	v_cvt_pk_bf16_f32 v17, v12, v13
	v_cvt_pk_bf16_f32 v16, v10, v11
	v_pk_mul_f32 v[8:9], v[8:9], v[24:25]
	v_pk_mul_f32 v[6:7], v[6:7], v[22:23]
	v_lshlrev_b32_e32 v10, 16, v34
	v_and_b32_e32 v11, 0xffff0000, v34
	v_lshlrev_b32_e32 v12, 16, v35
	v_and_b32_e32 v13, 0xffff0000, v35
	v_pk_mul_f32 v[6:7], v[6:7], v[10:11]
	v_mul_f32_e32 v10, 0xbfb8aa3b, v2
	v_pk_mul_f32 v[8:9], v[8:9], v[12:13]
	v_mul_f32_e32 v11, 0xbfb8aa3b, v3
	v_mul_f32_e32 v12, 0xbfb8aa3b, v4
	v_mul_f32_e32 v13, 0xbfb8aa3b, v5
	v_exp_f32_e32 v10, v10
	v_exp_f32_e32 v11, v11
	v_exp_f32_e32 v12, v12
	v_exp_f32_e32 v13, v13
	v_add_f32_e32 v10, 1.0, v10
	v_add_f32_e32 v11, 1.0, v11
	v_add_f32_e32 v12, 1.0, v12
	v_add_f32_e32 v13, 1.0, v13
	v_rcp_f32_e32 v10, v10
	v_rcp_f32_e32 v12, v12
	v_rcp_f32_e32 v13, v13
	v_rcp_f32_e32 v11, v11
	v_pk_mul_f32 v[8:9], v[8:9], v[26:27] op_sel_hi:[1,0]
	v_pk_mul_f32 v[6:7], v[6:7], v[26:27] op_sel_hi:[1,0]
	v_pk_mul_f32 v[4:5], v[4:5], v[12:13]
	v_cvt_pk_bf16_f32 v6, v6, v7
	v_cvt_pk_bf16_f32 v7, v8, v9
	v_pk_mul_f32 v[2:3], v[2:3], v[10:11]
	v_lshlrev_b32_e32 v8, 16, v36
	v_and_b32_e32 v9, 0xffff0000, v36
	v_lshlrev_b32_e32 v10, 16, v37
	v_and_b32_e32 v11, 0xffff0000, v37
	v_pk_mul_f32 v[2:3], v[2:3], v[8:9]
	v_pk_mul_f32 v[4:5], v[4:5], v[10:11]
	v_pk_mul_f32 v[30:31], v[30:31], v[48:49] op_sel_hi:[1,0]
	v_pk_mul_f32 v[4:5], v[4:5], v[26:27] op_sel_hi:[1,0]
	v_pk_mul_f32 v[2:3], v[2:3], v[26:27] op_sel_hi:[1,0]
	v_cvt_pk_bf16_f32 v130, v30, v31
	v_cvt_pk_bf16_f32 v8, v2, v3
	v_cvt_pk_bf16_f32 v9, v4, v5
	global_store_dwordx4 v[42:43], v[6:9], off
	global_store_dwordx4 v[42:43], v[14:17], off offset:256
	global_store_dwordx4 v[152:153], v[18:21], off
	s_andn2_b64 vcc, exec, s[2:3]
	s_mov_b64 s[0:1], -1
	global_store_dwordx4 v[152:153], v[130:133], off offset:256
	s_cbranch_vccnz .LBB0_678
